# baseline (speedup 1.0000x reference)
; #define ROWLOOP _Pragma("unroll") for(int ai=0;ai<2;++ai) _Pragma("unroll") for(int m=0;m<4;++m)
; #define PK8(a0,a1,a2,a3,b0,b1,b2,b3) make_uint4(cvtpk2(a0,a1), cvtpk2(a2,a3), cvtpk2(b0,b1), cvtpk2(b2,b3))
; template <int EPI>
; __device__ __forceinline__ void gemm_run(const GD& c, const bool has_next, const GD& nx, const Ctx& e, bf16* shm, float* rs, float* rs_nxt, float* racc_) {
;     ...
;     ROWLOOP { const int lrow = LROW; const long row = brow + lrow; const float r = rs[lrow];
;       float a[2][4];
; #pragma unroll
;       for (int bj = 0; bj < 2; ++bj)
; #pragma unroll
;         for (int j = 0; j < 4; ++j) { float g = acc[ai][bj][m][0][j] * r, u = acc[ai][bj][m][1][j] * r; a[bj][j] = g * __builtin_amdgcn_rcpf(1.f + __expf(-g)) * u; }
;       *reinterpret_cast<uint4*>(e.act + row * 2688 + pn * 128 + wc * 32 + cq8) = PK8(a[0][0], a[0][1], a[0][2], a[0][3], a[1][0], a[1][1], a[1][2], a[1][3]);
;     }
.LBB0_274:
	v_mov_b32_e32 v140, v165
	s_lshl_b32 s11, s22, 10
	s_movk_i32 s12, 0xffc0
	v_and_b32_e32 v0, 15, v140
	v_ashrrev_i32_e32 v134, 2, v140
	s_add_i32 s11, s11, 0
	v_and_or_b32 v0, v134, s12, v0
	v_lshl_add_u32 v134, v0, 2, s11
	v_add_u32_e32 v137, 0x20000, v134
	ds_read2_b32 v[134:135], v137 offset1:16
	v_add_u32_e32 v136, s10, v0
	s_lshl_b32 s12, s25, 7
	s_movk_i32 s14, 0x1500
	s_ashr_i32 s13, s12, 31
	s_waitcnt lgkmcnt(0)
	v_pk_mul_f32 v[130:131], v[130:131], v[134:135] op_sel_hi:[1,0]
	v_pk_mul_f32 v[126:127], v[126:127], v[134:135] op_sel_hi:[1,0]
	v_mul_f32_e32 v0, 0xbfb8aa3b, v130
	v_exp_f32_e32 v0, v0
	v_pk_mul_f32 v[122:123], v[122:123], v[134:135] op_sel_hi:[1,0]
	v_pk_mul_f32 v[128:129], v[128:129], v[134:135] op_sel_hi:[1,0]
	v_pk_mul_f32 v[118:119], v[118:119], v[134:135] op_sel_hi:[1,0]
	v_add_f32_e32 v0, 1.0, v0
	v_rcp_f32_e32 v138, v0
	v_mul_f32_e32 v0, 0xbfb8aa3b, v131
	v_exp_f32_e32 v0, v0
	v_pk_mul_f32 v[120:121], v[120:121], v[134:135] op_sel_hi:[1,0]
	s_and_b64 vcc, exec, s[2:3]
	v_add_f32_e32 v0, 1.0, v0
	v_rcp_f32_e32 v139, v0
	s_nop 0
	v_pk_mul_f32 v[130:131], v[130:131], v[138:139]
	s_nop 0
	v_pk_mul_f32 v[126:127], v[126:127], v[130:131]
	v_pk_mul_f32 v[130:131], v[132:133], v[134:135] op_sel_hi:[1,0]
	s_nop 0
	v_mul_f32_e32 v0, 0xbfb8aa3b, v130
	v_exp_f32_e32 v0, v0
	s_nop 0
	v_add_f32_e32 v0, 1.0, v0
	v_rcp_f32_e32 v132, v0
	v_mul_f32_e32 v0, 0xbfb8aa3b, v131
	v_exp_f32_e32 v0, v0
	s_nop 0
	v_add_f32_e32 v0, 1.0, v0
	v_rcp_f32_e32 v133, v0
	v_mul_f32_e32 v0, 0xbfb8aa3b, v122
	v_exp_f32_e32 v0, v0
	v_pk_mul_f32 v[130:131], v[130:131], v[132:133]
	s_nop 0
	v_pk_mul_f32 v[128:129], v[128:129], v[130:131]
	v_add_f32_e32 v0, 1.0, v0
	v_rcp_f32_e32 v130, v0
	v_mul_f32_e32 v0, 0xbfb8aa3b, v123
	v_exp_f32_e32 v0, v0
	s_nop 0
	v_add_f32_e32 v0, 1.0, v0
	v_rcp_f32_e32 v131, v0
	s_nop 0
	v_pk_mul_f32 v[122:123], v[122:123], v[130:131]
	s_nop 0
	v_pk_mul_f32 v[118:119], v[118:119], v[122:123]
	v_pk_mul_f32 v[122:123], v[124:125], v[134:135] op_sel_hi:[1,0]
	s_nop 0
	v_mul_f32_e32 v0, 0xbfb8aa3b, v122
	v_exp_f32_e32 v0, v0
	s_nop 0
	v_add_f32_e32 v0, 1.0, v0
	v_rcp_f32_e32 v124, v0
	v_mul_f32_e32 v0, 0xbfb8aa3b, v123
	v_exp_f32_e32 v0, v0
	s_nop 0
	v_add_f32_e32 v0, 1.0, v0
	v_rcp_f32_e32 v125, v0
	v_and_b32_e32 v0, 0xc0, v140
	v_pk_mul_f32 v[122:123], v[122:123], v[124:125]
	s_nop 0
	v_pk_mul_f32 v[120:121], v[120:121], v[122:123]
	v_cvt_pk_bf16_f32 v124, v118, v119
	v_mov_b64_e32 v[118:119], s[8:9]
	v_cvt_pk_bf16_f32 v125, v120, v121
	v_mad_i64_i32 v[120:121], s[10:11], v136, s14, v[118:119]
	s_lshl_b64 s[10:11], s[12:13], 1
	s_nop 0
	v_lshl_add_u64 v[120:121], v[120:121], 0, s[10:11]
	v_cvt_pk_bf16_f32 v122, v126, v127
	v_lshl_add_u64 v[126:127], v[120:121], 0, v[0:1]
	v_and_b32_e32 v120, 48, v140
	v_mov_b32_e32 v121, v1
	v_cvt_pk_bf16_f32 v123, v128, v129
	v_lshl_add_u64 v[126:127], v[126:127], 0, v[120:121]
	global_store_dwordx4 v[126:127], v[122:125], off
	v_mov_b64_e32 v[250:251], v[126:127]
	v_mov_b32_e32 v246, 0x15000
	v_mov_b32_e32 v247, 0
	v_mov_b32_e32 v248, 0x69000
	v_mov_b32_e32 v249, 0
	s_nop 1
	v_add_u32_e32 v123, 16, v136
	v_mov_b32_e32 v122, v135
	v_pk_mul_f32 v[114:115], v[114:115], v[122:123] op_sel_hi:[1,0]
	v_pk_mul_f32 v[110:111], v[110:111], v[122:123] op_sel_hi:[1,0]
	v_mul_f32_e32 v124, 0xbfb8aa3b, v114
	v_mul_f32_e32 v125, 0xbfb8aa3b, v115
	v_exp_f32_e32 v124, v124
	v_exp_f32_e32 v125, v125
	v_pk_mul_f32 v[112:113], v[112:113], v[122:123] op_sel_hi:[1,0]
	v_pk_mul_f32 v[106:107], v[106:107], v[122:123] op_sel_hi:[1,0]
	v_add_f32_e32 v124, 1.0, v124
	v_add_f32_e32 v125, 1.0, v125
	v_rcp_f32_e32 v124, v124
	v_rcp_f32_e32 v125, v125
	v_pk_mul_f32 v[102:103], v[102:103], v[122:123] op_sel_hi:[1,0]
	v_pk_mul_f32 v[104:105], v[104:105], v[122:123] op_sel_hi:[1,0]
	v_pk_mul_f32 v[114:115], v[114:115], v[124:125]
	s_nop 0
	v_pk_mul_f32 v[110:111], v[110:111], v[114:115]
	v_pk_mul_f32 v[114:115], v[116:117], v[122:123] op_sel_hi:[1,0]
	s_nop 0
	v_mul_f32_e32 v116, 0xbfb8aa3b, v114
	v_mul_f32_e32 v117, 0xbfb8aa3b, v115
	v_exp_f32_e32 v116, v116
	v_exp_f32_e32 v117, v117
	v_add_f32_e32 v116, 1.0, v116
	v_add_f32_e32 v117, 1.0, v117
	v_rcp_f32_e32 v116, v116
	v_rcp_f32_e32 v117, v117
	s_nop 0
	v_pk_mul_f32 v[114:115], v[114:115], v[116:117]
	s_nop 0
	v_pk_mul_f32 v[112:113], v[112:113], v[114:115]
	v_mul_f32_e32 v114, 0xbfb8aa3b, v106
	v_mul_f32_e32 v115, 0xbfb8aa3b, v107
	v_exp_f32_e32 v114, v114
	v_exp_f32_e32 v115, v115
	v_add_f32_e32 v114, 1.0, v114
	v_add_f32_e32 v115, 1.0, v115
	v_rcp_f32_e32 v114, v114
	v_rcp_f32_e32 v115, v115
	s_nop 0
	v_pk_mul_f32 v[106:107], v[106:107], v[114:115]
	s_nop 0
	v_pk_mul_f32 v[106:107], v[102:103], v[106:107]
	v_pk_mul_f32 v[102:103], v[108:109], v[122:123] op_sel_hi:[1,0]
	s_nop 0
	v_mul_f32_e32 v108, 0xbfb8aa3b, v102
	v_mul_f32_e32 v109, 0xbfb8aa3b, v103
	v_exp_f32_e32 v108, v108
	v_exp_f32_e32 v109, v109
	v_add_f32_e32 v108, 1.0, v108
	v_add_f32_e32 v109, 1.0, v109
	v_rcp_f32_e32 v108, v108
	v_rcp_f32_e32 v109, v109
	s_nop 0
	v_pk_mul_f32 v[102:103], v[102:103], v[108:109]
	s_nop 0
	v_pk_mul_f32 v[108:109], v[104:105], v[102:103]
	v_cvt_pk_bf16_f32 v104, v106, v107
	v_cvt_pk_bf16_f32 v102, v110, v111
	v_cvt_pk_bf16_f32 v103, v112, v113
	v_cvt_pk_bf16_f32 v105, v108, v109
	v_lshl_add_u64 v[250:251], v[250:251], 0, v[246:247]
	global_store_dwordx4 v[250:251], v[102:105], off
	ds_read2_b32 v[102:103], v137 offset0:32 offset1:48
	v_add_u32_e32 v106, 32, v136
	s_waitcnt lgkmcnt(0)
; #define ROWLOOP _Pragma("unroll") for(int ai=0;ai<2;++ai) _Pragma("unroll") for(int m=0;m<4;++m)
; #define PK8(a0,a1,a2,a3,b0,b1,b2,b3) make_uint4(cvtpk2(a0,a1), cvtpk2(a2,a3), cvtpk2(b0,b1), cvtpk2(b2,b3))
; template <int EPI>
; __device__ __forceinline__ void gemm_run(const GD& c, const bool has_next, const GD& nx, const Ctx& e, bf16* shm, float* rs, float* rs_nxt, float* racc_) {
;     ...
;     ROWLOOP { const int lrow = LROW; const long row = brow + lrow; const float r = rs[lrow];
;       float a[2][4];
; #pragma unroll
;       for (int bj = 0; bj < 2; ++bj)
; #pragma unroll
;         for (int j = 0; j < 4; ++j) { float g = acc[ai][bj][m][0][j] * r, u = acc[ai][bj][m][1][j] * r; a[bj][j] = g * __builtin_amdgcn_rcpf(1.f + __expf(-g)) * u; }
;       *reinterpret_cast<uint4*>(e.act + row * 2688 + pn * 128 + wc * 32 + cq8) = PK8(a[0][0], a[0][1], a[0][2], a[0][3], a[1][0], a[1][1], a[1][2], a[1][3]);
;     }
	v_pk_mul_f32 v[98:99], v[98:99], v[102:103] op_sel_hi:[1,0]
	s_nop 0
	v_mul_f32_e32 v104, 0xbfb8aa3b, v98
	v_mul_f32_e32 v105, 0xbfb8aa3b, v99
	v_exp_f32_e32 v104, v104
	v_exp_f32_e32 v105, v105
	v_pk_mul_f32 v[94:95], v[94:95], v[102:103] op_sel_hi:[1,0]
	v_pk_mul_f32 v[96:97], v[96:97], v[102:103] op_sel_hi:[1,0]
	v_add_f32_e32 v104, 1.0, v104
	v_add_f32_e32 v105, 1.0, v105
	v_rcp_f32_e32 v104, v104
	v_rcp_f32_e32 v105, v105
	v_pk_mul_f32 v[90:91], v[90:91], v[102:103] op_sel_hi:[1,0]
	v_pk_mul_f32 v[86:87], v[86:87], v[102:103] op_sel_hi:[1,0]
	v_pk_mul_f32 v[88:89], v[88:89], v[102:103] op_sel_hi:[1,0]
	v_pk_mul_f32 v[98:99], v[98:99], v[104:105]
	s_nop 0
	v_pk_mul_f32 v[94:95], v[94:95], v[98:99]
	v_pk_mul_f32 v[98:99], v[100:101], v[102:103] op_sel_hi:[1,0]
	s_nop 0
	v_mul_f32_e32 v100, 0xbfb8aa3b, v98
	v_mul_f32_e32 v101, 0xbfb8aa3b, v99
	v_exp_f32_e32 v100, v100
	v_exp_f32_e32 v101, v101
	v_add_f32_e32 v100, 1.0, v100
	v_add_f32_e32 v101, 1.0, v101
	v_rcp_f32_e32 v100, v100
	v_rcp_f32_e32 v101, v101
	s_nop 0
	v_pk_mul_f32 v[98:99], v[98:99], v[100:101]
	s_nop 0
	v_pk_mul_f32 v[96:97], v[96:97], v[98:99]
	v_mul_f32_e32 v98, 0xbfb8aa3b, v90
	v_mul_f32_e32 v99, 0xbfb8aa3b, v91
	v_exp_f32_e32 v98, v98
	v_exp_f32_e32 v99, v99
	v_add_f32_e32 v98, 1.0, v98
	v_add_f32_e32 v99, 1.0, v99
	v_rcp_f32_e32 v98, v98
	v_rcp_f32_e32 v99, v99
	s_nop 0
	v_pk_mul_f32 v[90:91], v[90:91], v[98:99]
	s_nop 0
	v_pk_mul_f32 v[90:91], v[86:87], v[90:91]
	v_pk_mul_f32 v[86:87], v[92:93], v[102:103] op_sel_hi:[1,0]
	s_nop 0
	v_mul_f32_e32 v92, 0xbfb8aa3b, v86
	v_mul_f32_e32 v93, 0xbfb8aa3b, v87
	v_exp_f32_e32 v92, v92
	v_exp_f32_e32 v93, v93
	v_add_f32_e32 v92, 1.0, v92
	v_add_f32_e32 v93, 1.0, v93
	v_rcp_f32_e32 v92, v92
	v_rcp_f32_e32 v93, v93
	s_nop 0
	v_pk_mul_f32 v[86:87], v[86:87], v[92:93]
	s_nop 0
	v_pk_mul_f32 v[92:93], v[88:89], v[86:87]
	v_cvt_pk_bf16_f32 v88, v90, v91
	v_cvt_pk_bf16_f32 v86, v94, v95
	v_cvt_pk_bf16_f32 v87, v96, v97
	v_cvt_pk_bf16_f32 v89, v92, v93
	v_lshl_add_u64 v[250:251], v[250:251], 0, v[246:247]
	global_store_dwordx4 v[250:251], v[86:89], off
	s_nop 1
	v_add_u32_e32 v87, 48, v136
	v_mov_b32_e32 v86, v103
	v_pk_mul_f32 v[82:83], v[82:83], v[86:87] op_sel_hi:[1,0]
	v_pk_mul_f32 v[78:79], v[78:79], v[86:87] op_sel_hi:[1,0]
	v_mul_f32_e32 v88, 0xbfb8aa3b, v82
	v_mul_f32_e32 v89, 0xbfb8aa3b, v83
	v_exp_f32_e32 v88, v88
	v_exp_f32_e32 v89, v89
	v_pk_mul_f32 v[80:81], v[80:81], v[86:87] op_sel_hi:[1,0]
	v_pk_mul_f32 v[74:75], v[74:75], v[86:87] op_sel_hi:[1,0]
	v_add_f32_e32 v88, 1.0, v88
	v_add_f32_e32 v89, 1.0, v89
	v_rcp_f32_e32 v88, v88
	v_rcp_f32_e32 v89, v89
	v_pk_mul_f32 v[70:71], v[70:71], v[86:87] op_sel_hi:[1,0]
	v_pk_mul_f32 v[72:73], v[72:73], v[86:87] op_sel_hi:[1,0]
	v_pk_mul_f32 v[82:83], v[82:83], v[88:89]
	s_nop 0
	v_pk_mul_f32 v[78:79], v[78:79], v[82:83]
	v_pk_mul_f32 v[82:83], v[84:85], v[86:87] op_sel_hi:[1,0]
	s_nop 0
	v_mul_f32_e32 v84, 0xbfb8aa3b, v82
	v_mul_f32_e32 v85, 0xbfb8aa3b, v83
	v_exp_f32_e32 v84, v84
	v_exp_f32_e32 v85, v85
	v_add_f32_e32 v84, 1.0, v84
	v_add_f32_e32 v85, 1.0, v85
	v_rcp_f32_e32 v84, v84
	v_rcp_f32_e32 v85, v85
	s_nop 0
	v_pk_mul_f32 v[82:83], v[82:83], v[84:85]
	s_nop 0
	v_pk_mul_f32 v[80:81], v[80:81], v[82:83]
	v_mul_f32_e32 v82, 0xbfb8aa3b, v74
	v_mul_f32_e32 v83, 0xbfb8aa3b, v75
	v_exp_f32_e32 v82, v82
	v_exp_f32_e32 v83, v83
	v_add_f32_e32 v82, 1.0, v82
	v_add_f32_e32 v83, 1.0, v83
	v_rcp_f32_e32 v82, v82
	v_rcp_f32_e32 v83, v83
	s_nop 0
	v_pk_mul_f32 v[74:75], v[74:75], v[82:83]
	s_nop 0
	v_pk_mul_f32 v[74:75], v[70:71], v[74:75]
	v_pk_mul_f32 v[70:71], v[76:77], v[86:87] op_sel_hi:[1,0]
	s_nop 0
	v_mul_f32_e32 v76, 0xbfb8aa3b, v70
	v_mul_f32_e32 v77, 0xbfb8aa3b, v71
	v_exp_f32_e32 v76, v76
	v_exp_f32_e32 v77, v77
	v_add_f32_e32 v76, 1.0, v76
	v_add_f32_e32 v77, 1.0, v77
	v_rcp_f32_e32 v76, v76
	v_rcp_f32_e32 v77, v77
	s_nop 0
	v_pk_mul_f32 v[70:71], v[70:71], v[76:77]
	s_nop 0
	v_pk_mul_f32 v[76:77], v[72:73], v[70:71]
	v_cvt_pk_bf16_f32 v72, v74, v75
	v_cvt_pk_bf16_f32 v70, v78, v79
	v_cvt_pk_bf16_f32 v71, v80, v81
	v_cvt_pk_bf16_f32 v73, v76, v77
	v_lshl_add_u64 v[250:251], v[250:251], 0, v[246:247]
	global_store_dwordx4 v[250:251], v[70:73], off
	ds_read2_b32 v[70:71], v137 offset0:128 offset1:144
	v_add_u32_e32 v74, 0x80, v136
	s_waitcnt lgkmcnt(0)
; #define ROWLOOP _Pragma("unroll") for(int ai=0;ai<2;++ai) _Pragma("unroll") for(int m=0;m<4;++m)
; #define PK8(a0,a1,a2,a3,b0,b1,b2,b3) make_uint4(cvtpk2(a0,a1), cvtpk2(a2,a3), cvtpk2(b0,b1), cvtpk2(b2,b3))
; template <int EPI>
; __device__ __forceinline__ void gemm_run(const GD& c, const bool has_next, const GD& nx, const Ctx& e, bf16* shm, float* rs, float* rs_nxt, float* racc_) {
;     ...
;     ROWLOOP { const int lrow = LROW; const long row = brow + lrow; const float r = rs[lrow];
;       float a[2][4];
; #pragma unroll
;       for (int bj = 0; bj < 2; ++bj)
; #pragma unroll
;         for (int j = 0; j < 4; ++j) { float g = acc[ai][bj][m][0][j] * r, u = acc[ai][bj][m][1][j] * r; a[bj][j] = g * __builtin_amdgcn_rcpf(1.f + __expf(-g)) * u; }
;       *reinterpret_cast<uint4*>(e.act + row * 2688 + pn * 128 + wc * 32 + cq8) = PK8(a[0][0], a[0][1], a[0][2], a[0][3], a[1][0], a[1][1], a[1][2], a[1][3]);
;     }
	v_pk_mul_f32 v[66:67], v[66:67], v[70:71] op_sel_hi:[1,0]
	s_nop 0
	v_mul_f32_e32 v72, 0xbfb8aa3b, v66
	v_mul_f32_e32 v73, 0xbfb8aa3b, v67
	v_exp_f32_e32 v72, v72
	v_exp_f32_e32 v73, v73
	v_pk_mul_f32 v[62:63], v[62:63], v[70:71] op_sel_hi:[1,0]
	v_pk_mul_f32 v[64:65], v[64:65], v[70:71] op_sel_hi:[1,0]
	v_add_f32_e32 v72, 1.0, v72
	v_add_f32_e32 v73, 1.0, v73
	v_rcp_f32_e32 v72, v72
	v_rcp_f32_e32 v73, v73
	v_pk_mul_f32 v[58:59], v[58:59], v[70:71] op_sel_hi:[1,0]
	v_pk_mul_f32 v[54:55], v[54:55], v[70:71] op_sel_hi:[1,0]
	v_pk_mul_f32 v[56:57], v[56:57], v[70:71] op_sel_hi:[1,0]
	v_pk_mul_f32 v[66:67], v[66:67], v[72:73]
	s_nop 0
	v_pk_mul_f32 v[62:63], v[62:63], v[66:67]
	v_pk_mul_f32 v[66:67], v[68:69], v[70:71] op_sel_hi:[1,0]
	s_nop 0
	v_mul_f32_e32 v68, 0xbfb8aa3b, v66
	v_mul_f32_e32 v69, 0xbfb8aa3b, v67
	v_exp_f32_e32 v68, v68
	v_exp_f32_e32 v69, v69
	v_add_f32_e32 v68, 1.0, v68
	v_add_f32_e32 v69, 1.0, v69
	v_rcp_f32_e32 v68, v68
	v_rcp_f32_e32 v69, v69
	s_nop 0
	v_pk_mul_f32 v[66:67], v[66:67], v[68:69]
	s_nop 0
	v_pk_mul_f32 v[64:65], v[64:65], v[66:67]
	v_mul_f32_e32 v66, 0xbfb8aa3b, v58
	v_mul_f32_e32 v67, 0xbfb8aa3b, v59
	v_exp_f32_e32 v66, v66
	v_exp_f32_e32 v67, v67
	v_add_f32_e32 v66, 1.0, v66
	v_add_f32_e32 v67, 1.0, v67
	v_rcp_f32_e32 v66, v66
	v_rcp_f32_e32 v67, v67
	s_nop 0
	v_pk_mul_f32 v[58:59], v[58:59], v[66:67]
	s_nop 0
	v_pk_mul_f32 v[58:59], v[54:55], v[58:59]
	v_pk_mul_f32 v[54:55], v[60:61], v[70:71] op_sel_hi:[1,0]
	s_nop 0
	v_mul_f32_e32 v60, 0xbfb8aa3b, v54
	v_mul_f32_e32 v61, 0xbfb8aa3b, v55
	v_exp_f32_e32 v60, v60
	v_exp_f32_e32 v61, v61
	v_add_f32_e32 v60, 1.0, v60
	v_add_f32_e32 v61, 1.0, v61
	v_rcp_f32_e32 v60, v60
	v_rcp_f32_e32 v61, v61
	s_nop 0
	v_pk_mul_f32 v[54:55], v[54:55], v[60:61]
	s_nop 0
	v_pk_mul_f32 v[60:61], v[56:57], v[54:55]
	v_cvt_pk_bf16_f32 v56, v58, v59
	v_cvt_pk_bf16_f32 v54, v62, v63
	v_cvt_pk_bf16_f32 v55, v64, v65
	v_cvt_pk_bf16_f32 v57, v60, v61
	v_lshl_add_u64 v[250:251], v[250:251], 0, v[248:249]
	global_store_dwordx4 v[250:251], v[54:57], off
	s_nop 1
	v_add_u32_e32 v55, 0x90, v136
	v_mov_b32_e32 v54, v71
	v_pk_mul_f32 v[50:51], v[50:51], v[54:55] op_sel_hi:[1,0]
	v_pk_mul_f32 v[46:47], v[46:47], v[54:55] op_sel_hi:[1,0]
	v_mul_f32_e32 v56, 0xbfb8aa3b, v50
	v_mul_f32_e32 v57, 0xbfb8aa3b, v51
	v_exp_f32_e32 v56, v56
	v_exp_f32_e32 v57, v57
	v_pk_mul_f32 v[48:49], v[48:49], v[54:55] op_sel_hi:[1,0]
	v_pk_mul_f32 v[42:43], v[42:43], v[54:55] op_sel_hi:[1,0]
	v_add_f32_e32 v56, 1.0, v56
	v_add_f32_e32 v57, 1.0, v57
	v_rcp_f32_e32 v56, v56
	v_rcp_f32_e32 v57, v57
	v_pk_mul_f32 v[38:39], v[38:39], v[54:55] op_sel_hi:[1,0]
	v_pk_mul_f32 v[40:41], v[40:41], v[54:55] op_sel_hi:[1,0]
	v_pk_mul_f32 v[50:51], v[50:51], v[56:57]
	s_nop 0
	v_pk_mul_f32 v[46:47], v[46:47], v[50:51]
	v_pk_mul_f32 v[50:51], v[52:53], v[54:55] op_sel_hi:[1,0]
	s_nop 0
	v_mul_f32_e32 v52, 0xbfb8aa3b, v50
	v_mul_f32_e32 v53, 0xbfb8aa3b, v51
	v_exp_f32_e32 v52, v52
	v_exp_f32_e32 v53, v53
	v_add_f32_e32 v52, 1.0, v52
	v_add_f32_e32 v53, 1.0, v53
	v_rcp_f32_e32 v52, v52
	v_rcp_f32_e32 v53, v53
	s_nop 0
	v_pk_mul_f32 v[50:51], v[50:51], v[52:53]
	s_nop 0
	v_pk_mul_f32 v[48:49], v[48:49], v[50:51]
	v_mul_f32_e32 v50, 0xbfb8aa3b, v42
	v_mul_f32_e32 v51, 0xbfb8aa3b, v43
	v_exp_f32_e32 v50, v50
	v_exp_f32_e32 v51, v51
	v_add_f32_e32 v50, 1.0, v50
	v_add_f32_e32 v51, 1.0, v51
	v_rcp_f32_e32 v50, v50
	v_rcp_f32_e32 v51, v51
	s_nop 0
	v_pk_mul_f32 v[42:43], v[42:43], v[50:51]
	s_nop 0
	v_pk_mul_f32 v[42:43], v[38:39], v[42:43]
	v_pk_mul_f32 v[38:39], v[44:45], v[54:55] op_sel_hi:[1,0]
	s_nop 0
	v_mul_f32_e32 v44, 0xbfb8aa3b, v38
	v_mul_f32_e32 v45, 0xbfb8aa3b, v39
	v_exp_f32_e32 v44, v44
	v_exp_f32_e32 v45, v45
	v_add_f32_e32 v44, 1.0, v44
	v_add_f32_e32 v45, 1.0, v45
	v_rcp_f32_e32 v44, v44
	v_rcp_f32_e32 v45, v45
	s_nop 0
	v_pk_mul_f32 v[38:39], v[38:39], v[44:45]
	s_nop 0
	v_pk_mul_f32 v[44:45], v[40:41], v[38:39]
	v_cvt_pk_bf16_f32 v40, v42, v43
	v_cvt_pk_bf16_f32 v38, v46, v47
	v_cvt_pk_bf16_f32 v39, v48, v49
	v_cvt_pk_bf16_f32 v41, v44, v45
	v_lshl_add_u64 v[250:251], v[250:251], 0, v[246:247]
	global_store_dwordx4 v[250:251], v[38:41], off
	ds_read2_b32 v[38:39], v137 offset0:160 offset1:176
	v_add_u32_e32 v42, 0xa0, v136
	s_waitcnt lgkmcnt(0)
; #define RS_STORE(d, dst, ra) do { if (tidv < 256 && (d).rsmode) { float s_; \
;     if ((d).rsmode == 1) { s_ = (ra.x + ra.y) + (ra.z + ra.w); s_ = rsqrtf(s_ * (1.f / 1024.f) + EPS); } \
;     else if ((d).rsmode == 2) { s_ = ra.x + ra.y; s_ = rsqrtf(s_ * (1.f / 384.f) + EPS); } \
;     else { s_ = ra.z; s_ = rsqrtf(s_ * (1.f / 256.f) + EPS); } \
;     (dst)[tidv] = s_; } } while (0)
; #define ROWLOOP _Pragma("unroll") for(int ai=0;ai<2;++ai) _Pragma("unroll") for(int m=0;m<4;++m)
; #define PK8(a0,a1,a2,a3,b0,b1,b2,b3) make_uint4(cvtpk2(a0,a1), cvtpk2(a2,a3), cvtpk2(b0,b1), cvtpk2(b2,b3))
; template <int EPI>
; __device__ __forceinline__ void gemm_run(const GD& c, const bool has_next, const GD& nx, const Ctx& e, bf16* shm, float* rs, float* rs_nxt, float* racc_) {
;     ...
;     ROWLOOP { const int lrow = LROW; const long row = brow + lrow; const float r = rs[lrow];
;       float a[2][4];
; #pragma unroll
;       for (int bj = 0; bj < 2; ++bj)
; #pragma unroll
;         for (int j = 0; j < 4; ++j) { float g = acc[ai][bj][m][0][j] * r, u = acc[ai][bj][m][1][j] * r; a[bj][j] = g * __builtin_amdgcn_rcpf(1.f + __expf(-g)) * u; }
;       *reinterpret_cast<uint4*>(e.act + row * 2688 + pn * 128 + wc * 32 + cq8) = PK8(a[0][0], a[0][1], a[0][2], a[0][3], a[1][0], a[1][1], a[1][2], a[1][3]);
;     }
;     ...
;   if (has_next) { tidv = threadIdx.x; asm volatile("" : "+v"(tidv)); RS_STORE(nx, rs_nxt, nra); }
	v_pk_mul_f32 v[34:35], v[34:35], v[38:39] op_sel_hi:[1,0]
	s_nop 0
	v_mul_f32_e32 v40, 0xbfb8aa3b, v34
	v_mul_f32_e32 v41, 0xbfb8aa3b, v35
	v_exp_f32_e32 v40, v40
	v_exp_f32_e32 v41, v41
	v_pk_mul_f32 v[30:31], v[30:31], v[38:39] op_sel_hi:[1,0]
	v_pk_mul_f32 v[32:33], v[32:33], v[38:39] op_sel_hi:[1,0]
	v_add_f32_e32 v40, 1.0, v40
	v_add_f32_e32 v41, 1.0, v41
	v_rcp_f32_e32 v40, v40
	v_rcp_f32_e32 v41, v41
	v_pk_mul_f32 v[26:27], v[26:27], v[38:39] op_sel_hi:[1,0]
	v_pk_mul_f32 v[22:23], v[22:23], v[38:39] op_sel_hi:[1,0]
	v_pk_mul_f32 v[24:25], v[24:25], v[38:39] op_sel_hi:[1,0]
	v_pk_mul_f32 v[34:35], v[34:35], v[40:41]
	s_nop 0
	v_pk_mul_f32 v[30:31], v[30:31], v[34:35]
	v_pk_mul_f32 v[34:35], v[36:37], v[38:39] op_sel_hi:[1,0]
	s_nop 0
	v_mul_f32_e32 v36, 0xbfb8aa3b, v34
	v_mul_f32_e32 v37, 0xbfb8aa3b, v35
	v_exp_f32_e32 v36, v36
	v_exp_f32_e32 v37, v37
	v_add_f32_e32 v36, 1.0, v36
	v_add_f32_e32 v37, 1.0, v37
	v_rcp_f32_e32 v36, v36
	v_rcp_f32_e32 v37, v37
	s_nop 0
	v_pk_mul_f32 v[34:35], v[34:35], v[36:37]
	s_nop 0
	v_pk_mul_f32 v[32:33], v[32:33], v[34:35]
	v_mul_f32_e32 v34, 0xbfb8aa3b, v26
	v_mul_f32_e32 v35, 0xbfb8aa3b, v27
	v_exp_f32_e32 v34, v34
	v_exp_f32_e32 v35, v35
	v_add_f32_e32 v34, 1.0, v34
	v_add_f32_e32 v35, 1.0, v35
	v_rcp_f32_e32 v34, v34
	v_rcp_f32_e32 v35, v35
	s_nop 0
	v_pk_mul_f32 v[26:27], v[26:27], v[34:35]
	s_nop 0
	v_pk_mul_f32 v[26:27], v[22:23], v[26:27]
	v_pk_mul_f32 v[22:23], v[28:29], v[38:39] op_sel_hi:[1,0]
	s_nop 0
	v_mul_f32_e32 v28, 0xbfb8aa3b, v22
	v_mul_f32_e32 v29, 0xbfb8aa3b, v23
	v_exp_f32_e32 v28, v28
	v_exp_f32_e32 v29, v29
	v_add_f32_e32 v28, 1.0, v28
	v_add_f32_e32 v29, 1.0, v29
	v_rcp_f32_e32 v28, v28
	v_rcp_f32_e32 v29, v29
	s_nop 0
	v_pk_mul_f32 v[22:23], v[22:23], v[28:29]
	s_nop 0
	v_pk_mul_f32 v[28:29], v[24:25], v[22:23]
	v_cvt_pk_bf16_f32 v24, v26, v27
	v_cvt_pk_bf16_f32 v22, v30, v31
	v_cvt_pk_bf16_f32 v23, v32, v33
	v_cvt_pk_bf16_f32 v25, v28, v29
	v_lshl_add_u64 v[250:251], v[250:251], 0, v[246:247]
	global_store_dwordx4 v[250:251], v[22:25], off
	s_nop 1
	v_add_u32_e32 v23, 0xb0, v136
	v_mov_b32_e32 v22, v39
	v_pk_mul_f32 v[18:19], v[18:19], v[22:23] op_sel_hi:[1,0]
	v_pk_mul_f32 v[14:15], v[14:15], v[22:23] op_sel_hi:[1,0]
	v_mul_f32_e32 v24, 0xbfb8aa3b, v18
	v_mul_f32_e32 v25, 0xbfb8aa3b, v19
	v_exp_f32_e32 v24, v24
	v_exp_f32_e32 v25, v25
	v_pk_mul_f32 v[16:17], v[16:17], v[22:23] op_sel_hi:[1,0]
	v_pk_mul_f32 v[10:11], v[10:11], v[22:23] op_sel_hi:[1,0]
	v_add_f32_e32 v24, 1.0, v24
	v_add_f32_e32 v25, 1.0, v25
	v_rcp_f32_e32 v24, v24
	v_rcp_f32_e32 v25, v25
	v_pk_mul_f32 v[6:7], v[6:7], v[22:23] op_sel_hi:[1,0]
	v_pk_mul_f32 v[8:9], v[8:9], v[22:23] op_sel_hi:[1,0]
	v_pk_mul_f32 v[18:19], v[18:19], v[24:25]
	s_nop 0
	v_pk_mul_f32 v[14:15], v[14:15], v[18:19]
	v_pk_mul_f32 v[18:19], v[20:21], v[22:23] op_sel_hi:[1,0]
	s_nop 0
	v_mul_f32_e32 v20, 0xbfb8aa3b, v18
	v_mul_f32_e32 v21, 0xbfb8aa3b, v19
	v_exp_f32_e32 v20, v20
	v_exp_f32_e32 v21, v21
	v_add_f32_e32 v20, 1.0, v20
	v_add_f32_e32 v21, 1.0, v21
	v_rcp_f32_e32 v20, v20
	v_rcp_f32_e32 v21, v21
	s_nop 0
	v_pk_mul_f32 v[18:19], v[18:19], v[20:21]
	s_nop 0
	v_pk_mul_f32 v[16:17], v[16:17], v[18:19]
	v_mul_f32_e32 v18, 0xbfb8aa3b, v10
	v_mul_f32_e32 v19, 0xbfb8aa3b, v11
	v_exp_f32_e32 v18, v18
	v_exp_f32_e32 v19, v19
	v_add_f32_e32 v18, 1.0, v18
	v_add_f32_e32 v19, 1.0, v19
	v_rcp_f32_e32 v18, v18
	v_rcp_f32_e32 v19, v19
	s_nop 0
	v_pk_mul_f32 v[10:11], v[10:11], v[18:19]
	s_nop 0
	v_pk_mul_f32 v[10:11], v[6:7], v[10:11]
	v_pk_mul_f32 v[6:7], v[12:13], v[22:23] op_sel_hi:[1,0]
	s_nop 0
	v_mul_f32_e32 v12, 0xbfb8aa3b, v6
	v_mul_f32_e32 v13, 0xbfb8aa3b, v7
	v_exp_f32_e32 v12, v12
	v_exp_f32_e32 v13, v13
	v_add_f32_e32 v12, 1.0, v12
	v_add_f32_e32 v13, 1.0, v13
	v_rcp_f32_e32 v12, v12
	v_rcp_f32_e32 v13, v13
	s_nop 0
	v_pk_mul_f32 v[6:7], v[6:7], v[12:13]
	s_nop 0
	v_pk_mul_f32 v[12:13], v[8:9], v[6:7]
	v_cvt_pk_bf16_f32 v8, v10, v11
	v_cvt_pk_bf16_f32 v6, v14, v15
	v_cvt_pk_bf16_f32 v7, v16, v17
	v_cvt_pk_bf16_f32 v9, v12, v13
	s_mov_b64 s[10:11], -1
	v_lshl_add_u64 v[250:251], v[250:251], 0, v[246:247]
	global_store_dwordx4 v[250:251], v[6:9], off
	s_cbranch_vccnz .LBB0_257
	v_mov_b32_e32 v0, v165
	s_xor_b32 s22, s22, 1
	s_nop 0
	v_cmp_gt_i32_e32 vcc, s96, v0
	s_and_saveexec_b64 s[2:3], vcc
	s_xor_b64 s[2:3], exec, s[2:3]
	s_cbranch_execz .LBB0_256
	s_waitcnt vmcnt(0)
	v_mov_b32_e32 v6, v3
	v_mov_b32_e32 v7, v5
	v_mov_b32_e32 v3, v4
	v_pk_add_f32 v[2:3], v[2:3], v[6:7]
	s_lshl_b32 s10, s22, 10
	v_add_f32_e32 v2, v2, v3
	v_fmamk_f32 v2, v2, 0x3a800000, v164
	v_cmp_gt_f32_e32 vcc, s97, v2
	v_mul_f32_e32 v3, 0x4b800000, v2
	s_add_i32 s10, s10, 0
	v_cndmask_b32_e32 v2, v2, v3, vcc
	v_rsq_f32_e32 v2, v2
	v_lshl_add_u32 v0, v0, 2, s10
	v_add_u32_e32 v0, 0x20000, v0
	v_mul_f32_e32 v3, 0x45800000, v2
	v_cndmask_b32_e32 v2, v2, v3, vcc
	ds_write_b32 v0, v2
	s_branch .LBB0_256

; __device__ __forceinline__ void finishSM(f32x16& p0, f32x16& p1, float alpha, float& l_reg, bf16x8& pa0, bf16x8& pa1, bf16x8& pa2, bf16x8& pa3) {
; #pragma unroll
;   for (int r = 0; r < 16; ++r) p1[r] = __builtin_amdgcn_exp2f(p1[r]);
;   float ps = 0;
; #pragma unroll
;   for (int r = 0; r < 16; ++r) ps += p0[r];
; #pragma unroll
;   for (int r = 0; r < 16; ++r) ps += p1[r];
;   { auto rr = __builtin_amdgcn_permlane32_swap(__float_as_uint(ps), __float_as_uint(ps), false, false);
;     ps = __uint_as_float(rr[0]) + __uint_as_float(rr[1]); }
;   l_reg = l_reg * alpha + ps;
;     ...
;   PK4(p0, 0, pa0); PK4(p0, 8, pa1); PK4(p1, 0, pa2); PK4(p1, 8, pa3);
;     ...
; }
; template <int DQK>
; __device__ __forceinline__ void qkt(f32x16& p0, f32x16& p1, const bf16* Ks, const bf16x8* qr, int r32, int hi, int k0, int L) {
;   p0 = f32x16{}; p1 = f32x16{};
; #pragma unroll
;   for (int d0 = 0; d0 < DQK / 16; ++d0) { int cb = (d0 * 16 + hi * 8) * 2;
;     bf16x8 b0 = *reinterpret_cast<const bf16x8*>((const char*)Ks + KSWZ(r32, cb));
;     bf16x8 b1 = *reinterpret_cast<const bf16x8*>((const char*)Ks + KSWZ(32 + r32, cb));
;     p0 = __builtin_amdgcn_mfma_f32_32x32x16_bf16(b0, qr[d0], p0, 0, 0, 0);
;     p1 = __builtin_amdgcn_mfma_f32_32x32x16_bf16(b1, qr[d0], p1, 0, 0, 0); }
;   if (k0 + KVBLK > L) {
; #pragma unroll
;     for (int r = 0; r < 16; ++r) { const int key = k0 + crow(r, hi);
;       if (key >= L) p0[r] = -1e30f;
;       if (key + 32 >= L) p1[r] = -1e30f; }
;   }
; }
; __device__ __forceinline__ int v_st(int k, int c) { const int kk = (k & ~0xC) | ((k & 4) << 1) | ((k & 8) >> 1); return ((kk >> 3) * 4 + (c >> 5)) * 512 + ((kk & 7) * 32 + (c & 31)) * 2; }
; __device__ __forceinline__ int v_rd_base(int lane) { return ((lane & 3) << 3) | (((lane >> 2) & 3) << 6) | (((lane >> 4) & 1) << 5) | (((lane >> 5) & 1) << 8); }
; template <int OFF> __device__ __forceinline__ s16x4 tr_read(int vb) {
;   s16x4 r; asm volatile("ds_read_b64_tr_b16 %0, %1 offset:%2" : "=&v"(r) : "v"(vb), "i"(OFF) : "memory"); return r;
; }
; template <int D0> __device__ __forceinline__ void pv_one(f32x16& od, int vb, bf16x8 pa0, bf16x8 pa1, bf16x8 pa2, bf16x8 pa3) {
;   const s16x4 l0 = tr_read<v_rd_off(D0, 0, 0)>(vb), h0 = tr_read<v_rd_off(D0, 0, 1)>(vb), l1 = tr_read<v_rd_off(D0, 1, 0)>(vb), h1 = tr_read<v_rd_off(D0, 1, 1)>(vb);
.LBB0_832:
	s_and_saveexec_b64 s[2:3], s[8:9]
	s_cbranch_execz .LBB0_838
	s_add_i32 s6, s78, 64
	s_cmp_le_u32 s6, s79
	s_cbranch_scc0 .Lslow64a
	s_and_b64 vcc, exec, s[10:11]
	s_cbranch_vccz .Lslow64a
	ds_read_b128 v[222:225], v167 offset:49152
	ds_read_b128 v[226:229], v168 offset:49152
	ds_read_b128 v[230:233], v167 offset:57344
	ds_read_b128 v[234:237], v168 offset:57344
	ds_read_b128 v[238:241], v169 offset:49152
	ds_read_b128 v[242:245], v169 offset:57344
	ds_read_b128 v[246:249], v171 offset:49152
	ds_read_b128 v[250:253], v171 offset:57344
	v_cvt_pk_bf16_f32 v130, v50, v51
	v_cvt_pk_bf16_f32 v131, v52, v53
	v_cvt_pk_bf16_f32 v132, v54, v55
	v_cvt_pk_bf16_f32 v133, v56, v57
	v_cvt_pk_bf16_f32 v134, v58, v59
	v_cvt_pk_bf16_f32 v135, v60, v61
	v_cvt_pk_bf16_f32 v136, v62, v63
	v_cvt_pk_bf16_f32 v137, v64, v65
	s_waitcnt lgkmcnt(7)
	v_mfma_f32_32x32x16_bf16 v[66:81], v[222:225], v[98:101], 0
	ds_read_b64_tr_b16 v[186:187], v166 offset:0
	ds_read_b64_tr_b16 v[188:189], v166 offset:2048
	ds_read_b64_tr_b16 v[190:191], v166 offset:4096
	ds_read_b64_tr_b16 v[192:193], v166 offset:6144
	v_exp_f32_e32 v34, v34
	v_exp_f32_e32 v35, v35
	v_add_f32_e32 v208, 0, v50
	v_add_f32_e32 v208, v51, v208
	s_waitcnt lgkmcnt(8)
	v_mfma_f32_32x32x16_bf16 v[66:81], v[226:229], v[102:105], v[66:81]
	ds_read_b64_tr_b16 v[194:195], v166 offset:8192
	ds_read_b64_tr_b16 v[196:197], v166 offset:10240
	ds_read_b64_tr_b16 v[198:199], v166 offset:12288
	ds_read_b64_tr_b16 v[200:201], v166 offset:14336
	v_exp_f32_e32 v36, v36
	v_exp_f32_e32 v37, v37
	v_exp_f32_e32 v38, v38
	v_add_f32_e32 v208, v52, v208
	v_mfma_f32_32x32x16_bf16 v[82:97], v[230:233], v[98:101], 0
	v_exp_f32_e32 v39, v39
	v_exp_f32_e32 v40, v40
	v_add_f32_e32 v208, v53, v208
	v_add_f32_e32 v208, v54, v208
	v_mfma_f32_32x32x16_bf16 v[82:97], v[234:237], v[102:105], v[82:97]
	v_exp_f32_e32 v41, v41
	v_exp_f32_e32 v42, v42
	v_exp_f32_e32 v43, v43
	v_add_f32_e32 v208, v55, v208
	s_waitcnt lgkmcnt(8)
	v_mfma_f32_32x32x16_bf16 v[66:81], v[238:241], v[106:109], v[66:81]
	v_exp_f32_e32 v44, v44
	v_exp_f32_e32 v45, v45
	v_add_f32_e32 v208, v56, v208
	v_add_f32_e32 v208, v57, v208
	v_mfma_f32_32x32x16_bf16 v[82:97], v[242:245], v[106:109], v[82:97]
	ds_read_b64_tr_b16 v[222:223], v166 offset:512
	ds_read_b64_tr_b16 v[224:225], v166 offset:2560
	ds_read_b64_tr_b16 v[226:227], v166 offset:4608
	ds_read_b64_tr_b16 v[228:229], v166 offset:6656
	v_exp_f32_e32 v46, v46
	v_exp_f32_e32 v47, v47
	v_exp_f32_e32 v48, v48
	v_add_f32_e32 v208, v58, v208
	v_mfma_f32_32x32x16_bf16 v[66:81], v[246:249], v[110:113], v[66:81]
	v_exp_f32_e32 v49, v49
	v_cvt_pk_bf16_f32 v138, v34, v35
	v_cvt_pk_bf16_f32 v139, v36, v37
	v_cvt_pk_bf16_f32 v140, v38, v39
	v_add_f32_e32 v208, v59, v208
	v_mfma_f32_32x32x16_bf16 v[82:97], v[250:253], v[110:113], v[82:97]
	ds_read_b64_tr_b16 v[230:231], v166 offset:8704
	ds_read_b64_tr_b16 v[232:233], v166 offset:10752
	ds_read_b64_tr_b16 v[234:235], v166 offset:12800
	s_waitcnt lgkmcnt(14)
	ds_read_b64_tr_b16 v[236:237], v166 offset:14848
	v_cvt_pk_bf16_f32 v141, v40, v41
	v_cvt_pk_bf16_f32 v142, v42, v43
	v_cvt_pk_bf16_f32 v143, v44, v45
	v_cvt_pk_bf16_f32 v144, v46, v47
	v_cvt_pk_bf16_f32 v145, v48, v49
	v_add_f32_e32 v208, v60, v208
	v_add_f32_e32 v208, v61, v208
	s_or_b64 exec, exec, s[2:3]
	global_load_dwordx4 v[122:125], v211, s[80:81] offset:2048
	global_load_dwordx4 v[126:129], v210, s[74:75]
	s_and_saveexec_b64 s[2:3], s[8:9]
	s_waitcnt lgkmcnt(0)
	v_mfma_f32_32x32x16_bf16 v[2:17], v[130:133], v[186:189], v[2:17]
	v_add_f32_e32 v208, v62, v208
	v_add_f32_e32 v208, v63, v208
	v_add_f32_e32 v208, v64, v208
	v_exp_f32_e32 v66, v66
	v_exp_f32_e32 v67, v67
	v_mfma_f32_32x32x16_bf16 v[2:17], v[134:137], v[190:193], v[2:17]
	v_add_f32_e32 v208, v65, v208
	v_add_f32_e32 v208, v34, v208
	v_add_f32_e32 v208, v35, v208
	v_exp_f32_e32 v68, v68
	v_exp_f32_e32 v69, v69
	v_exp_f32_e32 v70, v70
	v_mfma_f32_32x32x16_bf16 v[2:17], v[138:141], v[194:197], v[2:17]
	v_add_f32_e32 v208, v36, v208
	v_add_f32_e32 v208, v37, v208
	v_add_f32_e32 v208, v38, v208
	v_exp_f32_e32 v71, v71
	v_exp_f32_e32 v72, v72
	v_mfma_f32_32x32x16_bf16 v[2:17], v[142:145], v[198:201], v[2:17]
	v_add_f32_e32 v208, v39, v208
	v_add_f32_e32 v208, v40, v208
	v_exp_f32_e32 v73, v73
	v_exp_f32_e32 v74, v74
	v_mfma_f32_32x32x16_bf16 v[18:33], v[130:133], v[222:225], v[18:33]
	v_add_f32_e32 v208, v41, v208
	v_add_f32_e32 v208, v42, v208
	v_add_f32_e32 v208, v43, v208
	v_exp_f32_e32 v75, v75
	v_exp_f32_e32 v76, v76
	v_mfma_f32_32x32x16_bf16 v[18:33], v[134:137], v[226:229], v[18:33]
	v_add_f32_e32 v208, v44, v208
	v_add_f32_e32 v208, v45, v208
	v_add_f32_e32 v208, v46, v208
	v_exp_f32_e32 v77, v77
	v_exp_f32_e32 v78, v78
	v_exp_f32_e32 v79, v79
	v_mfma_f32_32x32x16_bf16 v[18:33], v[138:141], v[230:233], v[18:33]
	v_add_f32_e32 v208, v47, v208
	v_add_f32_e32 v208, v48, v208
	v_add_f32_e32 v208, v49, v208
	v_exp_f32_e32 v80, v80
	v_exp_f32_e32 v81, v81
	v_add_f32_e32 v202, v202, v208
	v_mfma_f32_32x32x16_bf16 v[18:33], v[142:145], v[234:237], v[18:33]
	s_branch .LBB0_842

; __device__ __forceinline__ void finishSM(f32x16& p0, f32x16& p1, float alpha, float& l_reg, bf16x8& pa0, bf16x8& pa1, bf16x8& pa2, bf16x8& pa3) {
; #pragma unroll
;   for (int r = 0; r < 16; ++r) p1[r] = __builtin_amdgcn_exp2f(p1[r]);
;   float ps = 0;
; #pragma unroll
;   for (int r = 0; r < 16; ++r) ps += p0[r];
; #pragma unroll
;   for (int r = 0; r < 16; ++r) ps += p1[r];
;   { auto rr = __builtin_amdgcn_permlane32_swap(__float_as_uint(ps), __float_as_uint(ps), false, false);
;     ps = __uint_as_float(rr[0]) + __uint_as_float(rr[1]); }
;   l_reg = l_reg * alpha + ps;
;     ...
;   PK4(p0, 0, pa0); PK4(p0, 8, pa1); PK4(p1, 0, pa2); PK4(p1, 8, pa3);
;     ...
; }
; template <int DQK>
; __device__ __forceinline__ void qkt(f32x16& p0, f32x16& p1, const bf16* Ks, const bf16x8* qr, int r32, int hi, int k0, int L) {
;   p0 = f32x16{}; p1 = f32x16{};
; #pragma unroll
;   for (int d0 = 0; d0 < DQK / 16; ++d0) { int cb = (d0 * 16 + hi * 8) * 2;
;     bf16x8 b0 = *reinterpret_cast<const bf16x8*>((const char*)Ks + KSWZ(r32, cb));
;     bf16x8 b1 = *reinterpret_cast<const bf16x8*>((const char*)Ks + KSWZ(32 + r32, cb));
;     p0 = __builtin_amdgcn_mfma_f32_32x32x16_bf16(b0, qr[d0], p0, 0, 0, 0);
;     p1 = __builtin_amdgcn_mfma_f32_32x32x16_bf16(b1, qr[d0], p1, 0, 0, 0); }
;   if (k0 + KVBLK > L) {
; #pragma unroll
;     for (int r = 0; r < 16; ++r) { const int key = k0 + crow(r, hi);
;       if (key >= L) p0[r] = -1e30f;
;       if (key + 32 >= L) p1[r] = -1e30f; }
;   }
; }
; __device__ __forceinline__ int v_st(int k, int c) { const int kk = (k & ~0xC) | ((k & 4) << 1) | ((k & 8) >> 1); return ((kk >> 3) * 4 + (c >> 5)) * 512 + ((kk & 7) * 32 + (c & 31)) * 2; }
; __device__ __forceinline__ int v_rd_base(int lane) { return ((lane & 3) << 3) | (((lane >> 2) & 3) << 6) | (((lane >> 4) & 1) << 5) | (((lane >> 5) & 1) << 8); }
; template <int OFF> __device__ __forceinline__ s16x4 tr_read(int vb) {
;   s16x4 r; asm volatile("ds_read_b64_tr_b16 %0, %1 offset:%2" : "=&v"(r) : "v"(vb), "i"(OFF) : "memory"); return r;
; }
; template <int D0> __device__ __forceinline__ void pv_one(f32x16& od, int vb, bf16x8 pa0, bf16x8 pa1, bf16x8 pa2, bf16x8 pa3) {
;   const s16x4 l0 = tr_read<v_rd_off(D0, 0, 0)>(vb), h0 = tr_read<v_rd_off(D0, 0, 1)>(vb), l1 = tr_read<v_rd_off(D0, 1, 0)>(vb), h1 = tr_read<v_rd_off(D0, 1, 1)>(vb);
.Lfast64b_nl:
	s_and_saveexec_b64 s[6:7], s[8:9]
	s_waitcnt lgkmcnt(0)
	v_mfma_f32_32x32x16_bf16 v[2:17], v[130:133], v[186:189], v[2:17]
	v_add_f32_e32 v208, v78, v208
	v_add_f32_e32 v208, v79, v208
	v_add_f32_e32 v208, v80, v208
	v_exp_f32_e32 v50, v50
	v_exp_f32_e32 v51, v51
	v_mfma_f32_32x32x16_bf16 v[2:17], v[134:137], v[190:193], v[2:17]
	v_add_f32_e32 v208, v81, v208
	v_add_f32_e32 v208, v82, v208
	v_add_f32_e32 v208, v83, v208
	v_exp_f32_e32 v52, v52
	v_exp_f32_e32 v53, v53
	v_exp_f32_e32 v54, v54
	v_mfma_f32_32x32x16_bf16 v[2:17], v[138:141], v[194:197], v[2:17]
	v_add_f32_e32 v208, v84, v208
	v_add_f32_e32 v208, v85, v208
	v_add_f32_e32 v208, v86, v208
	v_exp_f32_e32 v55, v55
	v_exp_f32_e32 v56, v56
	v_mfma_f32_32x32x16_bf16 v[2:17], v[142:145], v[198:201], v[2:17]
	v_add_f32_e32 v208, v87, v208
	v_add_f32_e32 v208, v88, v208
	v_exp_f32_e32 v57, v57
	v_exp_f32_e32 v58, v58
	v_mfma_f32_32x32x16_bf16 v[18:33], v[130:133], v[222:225], v[18:33]
	v_add_f32_e32 v208, v89, v208
	v_add_f32_e32 v208, v90, v208
	v_add_f32_e32 v208, v91, v208
	v_exp_f32_e32 v59, v59
	v_exp_f32_e32 v60, v60
	v_mfma_f32_32x32x16_bf16 v[18:33], v[134:137], v[226:229], v[18:33]
	v_add_f32_e32 v208, v92, v208
	v_add_f32_e32 v208, v93, v208
	v_add_f32_e32 v208, v94, v208
	v_exp_f32_e32 v61, v61
	v_exp_f32_e32 v62, v62
	v_exp_f32_e32 v63, v63
	v_mfma_f32_32x32x16_bf16 v[18:33], v[138:141], v[230:233], v[18:33]
	v_add_f32_e32 v208, v95, v208
	v_add_f32_e32 v208, v96, v208
	v_add_f32_e32 v208, v97, v208
	v_exp_f32_e32 v64, v64
	v_exp_f32_e32 v65, v65
	v_add_f32_e32 v202, v202, v208
	v_mfma_f32_32x32x16_bf16 v[18:33], v[142:145], v[234:237], v[18:33]
	s_branch .LBB0_831

; __device__ __forceinline__ void finishSM(f32x16& p0, f32x16& p1, float alpha, float& l_reg, bf16x8& pa0, bf16x8& pa1, bf16x8& pa2, bf16x8& pa3) {
; #pragma unroll
;   for (int r = 0; r < 16; ++r) p1[r] = __builtin_amdgcn_exp2f(p1[r]);
;   float ps = 0;
; #pragma unroll
;   for (int r = 0; r < 16; ++r) ps += p0[r];
; #pragma unroll
;   for (int r = 0; r < 16; ++r) ps += p1[r];
;   { auto rr = __builtin_amdgcn_permlane32_swap(__float_as_uint(ps), __float_as_uint(ps), false, false);
;     ps = __uint_as_float(rr[0]) + __uint_as_float(rr[1]); }
;   l_reg = l_reg * alpha + ps;
;     ...
;   PK4(p0, 0, pa0); PK4(p0, 8, pa1); PK4(p1, 0, pa2); PK4(p1, 8, pa3);
;     ...
; }
; template <int DQK>
; __device__ __forceinline__ void qkt(f32x16& p0, f32x16& p1, const bf16* Ks, const bf16x8* qr, int r32, int hi, int k0, int L) {
;   p0 = f32x16{}; p1 = f32x16{};
; #pragma unroll
;   for (int d0 = 0; d0 < DQK / 16; ++d0) { int cb = (d0 * 16 + hi * 8) * 2;
;     bf16x8 b0 = *reinterpret_cast<const bf16x8*>((const char*)Ks + KSWZ(r32, cb));
;     bf16x8 b1 = *reinterpret_cast<const bf16x8*>((const char*)Ks + KSWZ(32 + r32, cb));
;     p0 = __builtin_amdgcn_mfma_f32_32x32x16_bf16(b0, qr[d0], p0, 0, 0, 0);
;     p1 = __builtin_amdgcn_mfma_f32_32x32x16_bf16(b1, qr[d0], p1, 0, 0, 0); }
;   if (k0 + KVBLK > L) {
; #pragma unroll
;     for (int r = 0; r < 16; ++r) { const int key = k0 + crow(r, hi);
;       if (key >= L) p0[r] = -1e30f;
;       if (key + 32 >= L) p1[r] = -1e30f; }
;   }
; }
; __device__ __forceinline__ int v_st(int k, int c) { const int kk = (k & ~0xC) | ((k & 4) << 1) | ((k & 8) >> 1); return ((kk >> 3) * 4 + (c >> 5)) * 512 + ((kk & 7) * 32 + (c & 31)) * 2; }
; __device__ __forceinline__ int v_rd_base(int lane) { return ((lane & 3) << 3) | (((lane >> 2) & 3) << 6) | (((lane >> 4) & 1) << 5) | (((lane >> 5) & 1) << 8); }
; template <int OFF> __device__ __forceinline__ s16x4 tr_read(int vb) {
;   s16x4 r; asm volatile("ds_read_b64_tr_b16 %0, %1 offset:%2" : "=&v"(r) : "v"(vb), "i"(OFF) : "memory"); return r;
; }
; template <int D0> __device__ __forceinline__ void pv_one(f32x16& od, int vb, bf16x8 pa0, bf16x8 pa1, bf16x8 pa2, bf16x8 pa3) {
;   const s16x4 l0 = tr_read<v_rd_off(D0, 0, 0)>(vb), h0 = tr_read<v_rd_off(D0, 0, 1)>(vb), l1 = tr_read<v_rd_off(D0, 1, 0)>(vb), h1 = tr_read<v_rd_off(D0, 1, 1)>(vb);
.Lfast96a_k2:
	s_or_b64 exec, exec, s[2:3]
	s_and_saveexec_b64 s[2:3], s[10:11]
	s_waitcnt lgkmcnt(0)
	v_mfma_f32_32x32x16_bf16 v[32:47], v[10:13], v[206:209], v[32:47]
	v_add_f32_e32 v0, v54, v0
	v_exp_f32_e32 v80, v80
	v_exp_f32_e32 v81, v81
	v_mfma_f32_32x32x16_bf16 v[32:47], v[152:155], v[210:213], v[32:47]
	v_add_f32_e32 v0, v55, v0
	v_add_f32_e32 v0, v56, v0
	v_exp_f32_e32 v82, v82
	v_exp_f32_e32 v83, v83
	v_exp_f32_e32 v84, v84
	v_mfma_f32_32x32x16_bf16 v[32:47], v[156:159], v[214:217], v[32:47]
	v_add_f32_e32 v0, v57, v0
	v_exp_f32_e32 v85, v85
	v_exp_f32_e32 v86, v86
	v_mfma_f32_32x32x16_bf16 v[32:47], v[160:163], v[218:221], v[32:47]
	v_add_f32_e32 v0, v58, v0
	v_add_f32_e32 v0, v59, v0
	v_exp_f32_e32 v87, v87
	v_exp_f32_e32 v88, v88
	v_mfma_f32_32x32x16_bf16 v[16:31], v[10:13], v[238:241], v[16:31]
	v_add_f32_e32 v0, v60, v0
	v_exp_f32_e32 v89, v89
	v_exp_f32_e32 v90, v90
	v_mfma_f32_32x32x16_bf16 v[16:31], v[152:155], v[242:245], v[16:31]
	v_add_f32_e32 v0, v61, v0
	v_add_f32_e32 v0, v62, v0
	v_exp_f32_e32 v91, v91
	v_exp_f32_e32 v92, v92
	v_exp_f32_e32 v93, v93
	v_mfma_f32_32x32x16_bf16 v[16:31], v[156:159], v[246:249], v[16:31]
	v_add_f32_e32 v0, v63, v0
	v_exp_f32_e32 v94, v94
	v_exp_f32_e32 v95, v95
	v_add_f32_e32 v186, v186, v0
	v_mfma_f32_32x32x16_bf16 v[16:31], v[160:163], v[250:253], v[16:31]
	s_branch .LBB0_895

; __device__ __forceinline__ void finishSM(f32x16& p0, f32x16& p1, float alpha, float& l_reg, bf16x8& pa0, bf16x8& pa1, bf16x8& pa2, bf16x8& pa3) {
; #pragma unroll
;   for (int r = 0; r < 16; ++r) p1[r] = __builtin_amdgcn_exp2f(p1[r]);
;   float ps = 0;
; #pragma unroll
;   for (int r = 0; r < 16; ++r) ps += p0[r];
; #pragma unroll
;   for (int r = 0; r < 16; ++r) ps += p1[r];
;   { auto rr = __builtin_amdgcn_permlane32_swap(__float_as_uint(ps), __float_as_uint(ps), false, false);
;     ps = __uint_as_float(rr[0]) + __uint_as_float(rr[1]); }
;   l_reg = l_reg * alpha + ps;
;     ...
;   PK4(p0, 0, pa0); PK4(p0, 8, pa1); PK4(p1, 0, pa2); PK4(p1, 8, pa3);
;     ...
; }
; template <int DQK>
; __device__ __forceinline__ void qkt(f32x16& p0, f32x16& p1, const bf16* Ks, const bf16x8* qr, int r32, int hi, int k0, int L) {
;   p0 = f32x16{}; p1 = f32x16{};
; #pragma unroll
;   for (int d0 = 0; d0 < DQK / 16; ++d0) { int cb = (d0 * 16 + hi * 8) * 2;
;     bf16x8 b0 = *reinterpret_cast<const bf16x8*>((const char*)Ks + KSWZ(r32, cb));
;     bf16x8 b1 = *reinterpret_cast<const bf16x8*>((const char*)Ks + KSWZ(32 + r32, cb));
;     p0 = __builtin_amdgcn_mfma_f32_32x32x16_bf16(b0, qr[d0], p0, 0, 0, 0);
;     p1 = __builtin_amdgcn_mfma_f32_32x32x16_bf16(b1, qr[d0], p1, 0, 0, 0); }
;   if (k0 + KVBLK > L) {
; #pragma unroll
;     for (int r = 0; r < 16; ++r) { const int key = k0 + crow(r, hi);
;       if (key >= L) p0[r] = -1e30f;
;       if (key + 32 >= L) p1[r] = -1e30f; }
;   }
; }
; __device__ __forceinline__ int v_st(int k, int c) { const int kk = (k & ~0xC) | ((k & 4) << 1) | ((k & 8) >> 1); return ((kk >> 3) * 4 + (c >> 5)) * 512 + ((kk & 7) * 32 + (c & 31)) * 2; }
; __device__ __forceinline__ int v_rd_base(int lane) { return ((lane & 3) << 3) | (((lane >> 2) & 3) << 6) | (((lane >> 4) & 1) << 5) | (((lane >> 5) & 1) << 8); }
; template <int OFF> __device__ __forceinline__ s16x4 tr_read(int vb) {
;   s16x4 r; asm volatile("ds_read_b64_tr_b16 %0, %1 offset:%2" : "=&v"(r) : "v"(vb), "i"(OFF) : "memory"); return r;
; }
; template <int D0> __device__ __forceinline__ void pv_one(f32x16& od, int vb, bf16x8 pa0, bf16x8 pa1, bf16x8 pa2, bf16x8 pa3) {
;   const s16x4 l0 = tr_read<v_rd_off(D0, 0, 0)>(vb), h0 = tr_read<v_rd_off(D0, 0, 1)>(vb), l1 = tr_read<v_rd_off(D0, 1, 0)>(vb), h1 = tr_read<v_rd_off(D0, 1, 1)>(vb);
.Lfast96b_nl:
	s_and_saveexec_b64 s[14:15], s[10:11]
	s_waitcnt lgkmcnt(0)
	v_mfma_f32_32x32x16_bf16 v[32:47], v[10:13], v[206:209], v[32:47]
	v_add_f32_e32 v0, v102, v0
	v_exp_f32_e32 v64, v64
	v_exp_f32_e32 v65, v65
	v_mfma_f32_32x32x16_bf16 v[32:47], v[152:155], v[210:213], v[32:47]
	v_add_f32_e32 v0, v103, v0
	v_add_f32_e32 v0, v104, v0
	v_exp_f32_e32 v66, v66
	v_exp_f32_e32 v67, v67
	v_exp_f32_e32 v68, v68
	v_mfma_f32_32x32x16_bf16 v[32:47], v[156:159], v[214:217], v[32:47]
	v_add_f32_e32 v0, v105, v0
	v_exp_f32_e32 v69, v69
	v_exp_f32_e32 v70, v70
	v_mfma_f32_32x32x16_bf16 v[32:47], v[160:163], v[218:221], v[32:47]
	v_add_f32_e32 v0, v106, v0
	v_add_f32_e32 v0, v107, v0
	v_exp_f32_e32 v71, v71
	v_exp_f32_e32 v72, v72
	v_mfma_f32_32x32x16_bf16 v[16:31], v[10:13], v[238:241], v[16:31]
	v_add_f32_e32 v0, v108, v0
	v_exp_f32_e32 v73, v73
	v_exp_f32_e32 v74, v74
	v_mfma_f32_32x32x16_bf16 v[16:31], v[152:155], v[242:245], v[16:31]
	v_add_f32_e32 v0, v109, v0
	v_add_f32_e32 v0, v110, v0
	v_exp_f32_e32 v75, v75
	v_exp_f32_e32 v76, v76
	v_exp_f32_e32 v77, v77
	v_mfma_f32_32x32x16_bf16 v[16:31], v[156:159], v[246:249], v[16:31]
	v_add_f32_e32 v0, v111, v0
	v_exp_f32_e32 v78, v78
	v_exp_f32_e32 v79, v79
	v_add_f32_e32 v186, v186, v0
	v_mfma_f32_32x32x16_bf16 v[16:31], v[160:163], v[250:253], v[16:31]
	s_branch .LBB0_911
